# MLA attention tile loop hand-rewritten: software-pipelined (PV(t-1)/QK(t+1) MFMAs interleaved with softmax(t) VALU), 4 LDS slots, prefetch distance 2
# speedup vs baseline: 1.2067x; 1.0134x over previous
; template <int DQK, int DV, int FLAGS, int qp, int kp, int vts, int op> ...
;     ...
;     const int qpos = q0 + 32 * wave + r32, qmin_w = q0 + 32 * wave, qmax_w = qmin_w + 31;
;     f32x16 o[NDB];
; #pragma unroll
;     for (int d = 0; d < NDB; ++d)
; #pragma unroll
;         for (int r = 0; r < 16; ++r) o[d][r] = 0.f;
;     float m = (FLAGS & AF_ROBUST) ? -1e30f : 0.f, l = 0.f;
;     f32x16 negm;
; #pragma unroll
;     for (int r = 0; r < 16; ++r) negm[r] = 0.f;
;     u32x4 kreg[KPT], vreg[VPT];
;     unsigned kgo[KPT], vgo[VPT], klo[KPT], vlo[VPT];
; #pragma unroll
;     for (int i = 0; i < KPT; ++i) { const int c = tid + i * NTHREADS; const int row = c / KC, cc = c % KC; kgo[i] = (unsigned)(row * kp + cc * 8) * 2u; klo[i] = (unsigned)(row * KROW + cc * 16); }
; #pragma unroll
;     for (int i = 0; i < VPT; ++i) { const int c = tid + i * NTHREADS; const int d = c >> 3, cc = c & 7; vgo[i] = (unsigned)(d * vts + cc * 8) * 2u; vlo[i] = (unsigned)(KT_BYTES + d * VROW + cc * 16); }
;     ...
;     ATT_GLOAD((FLAGS & AF_REV) ? kt_hi - 1 : kt_lo); ATT_LSTORE(0);
;     __syncthreads();
;     bool started = false;
;     const int prow = (r32 & ~12) | ((r32 & 4) << 1) | ((r32 & 8) >> 1);
;     const int ntile = kt_hi - kt_lo;
;     ...
;         if (!skip) {
;             const LAS unsigned char* kb = lds + cur * BUF + prow * KROW + 16 * hi;
;             const LAS unsigned char* vb = lds + cur * BUF + KT_BYTES + r32 * VROW + 16 * hi;
;             f32x16 p0, p1;
;             bf16x8 kf[2][4];
; #pragma unroll
;             for (int i = 0; i < 2; ++i) { kf[0][2 * i] = *(const LAS bf16x8*)(kb + i * 32); kf[0][2 * i + 1] = *(const LAS bf16x8*)(kb + 32 * KROW + i * 32); }
;             const int nrel = qpos - kv0 - 8 * hi;
;             if (FLAGS & AF_ALIBI) { const float ab = -slope2 * (float)nrel - ((FLAGS & AF_ROBUST) ? 0.f : m);
; #pragma unroll
;                 for (int r = 0; r < 16; ++r) { const float c = (float)(16 * (r >> 3) + (r & 7)); p0[r] = __builtin_fmaf(slope2, c, ab); p1[r] = __builtin_fmaf(slope2, c + 32.f, ab); }
;             } else if (FLAGS & AF_ROBUST) {
; #pragma unroll
;                 for (int r = 0; r < 16; ++r) { p0[r] = 0.f; p1[r] = 0.f; }
;             } else { p0 = negm; p1 = negm; }
;             __builtin_amdgcn_sched_barrier(0);
; #pragma unroll
;             for (int c = 0; c < ND0 / 2; ++c) {
;                 if (c + 1 < ND0 / 2) {
; #pragma unroll
.LBB0_536:
	s_andn2_b64 vcc, exec, s[12:13]
	v_lshlrev_b32_e32 v170, 3, v19
	s_cbranch_vccnz .LBB0_524
	s_and_b32 s87, s19, 0xffffffe0
	s_add_i32 s16, s16, s17
	s_add_i32 s87, s87, s3
	s_lshl_b32 s15, s2, 2
	s_lshl_b32 s12, s16, 17
	s_or_b32 s88, s87, 31
	s_add_i32 s2, s15, 4
	s_bfe_u32 s17, s16, 0x30004
	s_and_b32 s12, s12, 0xe00000
	s_add_u32 s12, s14, s12
	s_addc_u32 s13, 0, 0
	s_add_u32 s12, s93, s12
	v_readlane_b32 s14, v252, 61
	v_mov_b32_e32 v21, v1
	s_addc_u32 s13, s14, s13
	s_mulk_i32 s17, 0xc0
	v_and_b32_e32 v22, 31, v17
	v_and_b32_e32 v19, 19, v17
	v_lshlrev_b32_e32 v23, 1, v17
	v_lshrrev_b32_e32 v17, 1, v17
	v_lshl_add_u64 v[176:177], s[12:13], 0, v[20:21]
	s_add_u32 s12, s18, s17
	v_and_b32_e32 v23, 8, v23
	v_and_b32_e32 v17, 4, v17
	s_addc_u32 s13, 0, 0
	v_readlane_b32 s14, v252, 63
	v_or3_b32 v17, v19, v23, v17
	s_add_u32 s12, s14, s12
	v_readlane_b32 s14, v253, 1
	v_mul_u32_u24_e32 v169, 0xd0, v17
	v_mul_u32_u24_e32 v171, 0x90, v22
	v_mov_b32_e32 v17, v1
	v_mov_b32_e32 v19, v1
	v_add_u32_e32 v22, s87, v22
	s_addc_u32 s13, s14, s13
	v_mov_b32_e32 v32, v1
	v_mov_b32_e32 v33, v1
	v_sub_u32_e32 v173, v22, v170
	v_lshl_add_u64 v[178:179], s[12:13], 0, v[16:17]
	v_lshl_add_u64 v[180:181], s[12:13], 0, v[18:19]
	v_mov_b32_e32 v34, v1
	v_mov_b32_e32 v35, v1
	v_mov_b32_e32 v36, v1
	v_mov_b32_e32 v37, v1
	v_mov_b32_e32 v38, v1
	v_mov_b32_e32 v39, v1
	v_mov_b32_e32 v40, v1
	v_mov_b32_e32 v41, v1
	v_mov_b32_e32 v42, v1
	v_mov_b32_e32 v43, v1
	v_mov_b32_e32 v44, v1
	v_mov_b32_e32 v45, v1
	v_mov_b32_e32 v46, v1
	v_mov_b32_e32 v47, v1
	v_mov_b32_e32 v183, 0
	v_mov_b64_e32 v[16:17], v[32:33]
	s_mov_b64 s[0:1], s[90:91]
	s_mov_b32 s3, 1
	s_xor_b32 s90, s15, -4
	s_mov_b64 s[82:83], 0
	s_mov_b32 s91, 63
	v_mov_b64_e32 v[18:19], v[34:35]
	v_mov_b64_e32 v[20:21], v[36:37]
	v_mov_b64_e32 v[22:23], v[38:39]
	v_mov_b64_e32 v[24:25], v[40:41]
	v_mov_b64_e32 v[26:27], v[42:43]
	v_mov_b64_e32 v[28:29], v[44:45]
	v_mov_b64_e32 v[30:31], v[46:47]
	v_mov_b32_e32 v175, 0
	v_mov_b32_e32 v48, 0
	v_mov_b32_e32 v49, v183
	v_mov_b32_e32 v50, v183
	v_mov_b32_e32 v51, v183
	v_mov_b32_e32 v52, v183
	v_mov_b32_e32 v53, v183
	v_mov_b32_e32 v54, v183
	v_mov_b32_e32 v55, v183
	v_mov_b32_e32 v56, v183
	v_mov_b32_e32 v57, v183
	v_mov_b32_e32 v58, v183
	v_mov_b32_e32 v59, v183
	v_mov_b32_e32 v60, v183
	v_mov_b32_e32 v61, v183
	v_mov_b32_e32 v62, v183
	v_mov_b32_e32 v63, v183
	s_andn2_b64 vcc, exec, s[4:5]
	s_cbranch_vccnz .Lq_fallback
	s_and_saveexec_b64 s[14:15], s[10:11]
	global_load_dwordx4 v[144:147], v[180:181], off
	s_or_b64 exec, exec, s[14:15]
	global_load_dwordx4 v[140:143], v[178:179], off
	global_load_dwordx4 v[148:151], v[176:177], off
	s_mov_b64 s[14:15], 0x80
	v_lshl_add_u64 v[176:177], v[176:177], 0, s[14:15]
	v_lshl_add_u64 v[178:179], v[178:179], 0, s[96:97]
	v_lshl_add_u64 v[180:181], v[180:181], 0, s[96:97]
	s_movk_i32 s16, 0x5800
	s_waitcnt vmcnt(0)
	v_add_u32_e32 v209, s16, v14
	v_add_u32_e32 v210, s16, v174
	v_add_u32_e32 v211, s16, v172
	ds_write_b128 v209, v[140:143]
	ds_write_b128 v210, v[148:151] offset:13312
	s_and_saveexec_b64 s[14:15], s[10:11]
	ds_write_b128 v211, v[144:147]
	s_or_b64 exec, exec, s[14:15]
	s_and_saveexec_b64 s[14:15], s[10:11]
	global_load_dwordx4 v[144:147], v[180:181], off
	s_or_b64 exec, exec, s[14:15]
	global_load_dwordx4 v[140:143], v[178:179], off
	global_load_dwordx4 v[148:151], v[176:177], off
	s_mov_b64 s[14:15], 0x80
	v_lshl_add_u64 v[176:177], v[176:177], 0, s[14:15]
	v_lshl_add_u64 v[178:179], v[178:179], 0, s[96:97]
	v_lshl_add_u64 v[180:181], v[180:181], 0, s[96:97]
	s_lshr_b32 s20, s88, 6
	s_add_i32 s20, s20, 1
	s_min_i32 s20, s20, s2
	s_mov_b32 s3, 0
	s_waitcnt lgkmcnt(0)
	s_barrier
	v_add_u32_e32 v206, v169, v0
	ds_read_b128 v[96:99], v206
	ds_read_b128 v[104:107], v206 offset:6656
	ds_read_b128 v[100:103], v206 offset:32
	ds_read_b128 v[108:111], v206 offset:6688
	ds_read_b128 v[112:115], v206 offset:64
	ds_read_b128 v[120:123], v206 offset:6720
	ds_read_b128 v[116:119], v206 offset:96
	ds_read_b128 v[124:127], v206 offset:6752
	s_waitcnt lgkmcnt(4)
	v_mfma_f32_32x32x16_bf16 v[64:79], v[96:99], v[2:5], v[48:63]
	v_mfma_f32_32x32x16_bf16 v[80:95], v[104:107], v[2:5], v[48:63]
	v_mfma_f32_32x32x16_bf16 v[64:79], v[100:103], v[6:9], v[64:79]
	v_mfma_f32_32x32x16_bf16 v[80:95], v[108:111], v[6:9], v[80:95]
	ds_read_b128 v[96:99], v206 offset:128
	ds_read_b128 v[104:107], v206 offset:6784
	ds_read_b128 v[100:103], v206 offset:160
	ds_read_b128 v[108:111], v206 offset:6816
	s_waitcnt lgkmcnt(4)
	v_mfma_f32_32x32x16_bf16 v[64:79], v[112:115], v[10:13], v[64:79]
	v_mfma_f32_32x32x16_bf16 v[80:95], v[120:123], v[10:13], v[80:95]
	v_mfma_f32_32x32x16_bf16 v[64:79], v[116:119], v[128:131], v[64:79]
	v_mfma_f32_32x32x16_bf16 v[80:95], v[124:127], v[128:131], v[80:95]
	s_waitcnt lgkmcnt(0)
	v_mfma_f32_32x32x16_bf16 v[64:79], v[96:99], v[132:135], v[64:79]
	v_mfma_f32_32x32x16_bf16 v[80:95], v[104:107], v[132:135], v[80:95]
	v_mfma_f32_32x32x16_bf16 v[64:79], v[100:103], v[136:139], v[64:79]
	v_mfma_f32_32x32x16_bf16 v[80:95], v[108:111], v[136:139], v[80:95]
; #define LAS __attribute__((address_space(3)))
; template <int DQK, int DV, int FLAGS, int qp, int kp, int vts, int op> ...
;     ...
;             __builtin_amdgcn_sched_barrier(0);
; #pragma unroll
;             for (int c = 0; c < ND0 / 2; ++c) {
;                 if (c + 1 < ND0 / 2) {
; #pragma unroll
;                     for (int i = 0; i < 2; ++i) { kf[(c + 1) & 1][2 * i] = *(const LAS bf16x8*)(kb + (2 * c + 2 + i) * 32); kf[(c + 1) & 1][2 * i + 1] = *(const LAS bf16x8*)(kb + 32 * KROW + (2 * c + 2 + i) * 32); }
;                 }
; #pragma unroll
;                 for (int i = 0; i < 2; ++i) {
;                     p0 = __builtin_amdgcn_mfma_f32_32x32x16_bf16(kf[c & 1][2 * i], qr[2 * c + i], p0, 0, 0, 0);
;                     p1 = __builtin_amdgcn_mfma_f32_32x32x16_bf16(kf[c & 1][2 * i + 1], qr[2 * c + i], p1, 0, 0, 0);
;                 }
;                 __builtin_amdgcn_sched_barrier(0);
;             }
;             if (more) ATT_GLOAD((FLAGS & AF_REV) ? t - 1 : t + 1);
;     ...
;             f32x2 rs2 = {0.f, 0.f};
; #pragma unroll
;             for (int r = 0; r < 16; ++r) { p0[r] = __builtin_amdgcn_exp2f(p0[r]); p1[r] = __builtin_amdgcn_exp2f(p1[r]); }
; #pragma unroll
;             for (int r = 0; r < 16; r += 2) { rs2 += (f32x2){p0[r], p0[r + 1]}; rs2 += (f32x2){p1[r], p1[r + 1]}; }
;             l += rs2.x + rs2.y;
;             bf16x8 pf[4];
;             pf[0] = pack_bf16x8(p0, 0); pf[1] = pack_bf16x8(p0, 8); pf[2] = pack_bf16x8(p1, 0); pf[3] = pack_bf16x8(p1, 8);
;             __builtin_amdgcn_sched_barrier(0);
; #pragma unroll
;             for (int d = 0; d < NDB; ++d) {
;                 if (d + 1 < NDB) {
; #pragma unroll
;                     for (int ks = 0; ks < 4; ++ks) vf[(d + 1) & 1][ks] = *(const LAS bf16x8*)(vb + (d + 1) * 32 * VROW + ks * 32);
;                 }
; #pragma unroll
;                 for (int ks = 0; ks < 4; ++ks) o[d] = __builtin_amdgcn_mfma_f32_32x32x16_bf16(vf[d & 1][ks], pf[ks], o[d], 0, 0, 0);
;                 __builtin_amdgcn_sched_barrier(0);
;             }
.Lq_top0:
	s_cmp_eq_u32 s3, 0
	s_cbranch_scc1 .Lq_gen0
	s_add_i32 s13, s3, 1
	s_cmp_ge_i32 s13, s20
	s_cbranch_scc1 .Lq_gen0
	s_add_i32 s12, s3, 1
	s_and_b32 s12, s12, 3
	s_mulk_i32 s12, 0x5800
	v_add3_u32 v206, s12, v169, v0
	ds_read_b128 v[96:99], v206
	ds_read_b128 v[104:107], v206 offset:6656
	ds_read_b128 v[100:103], v206 offset:32
	ds_read_b128 v[108:111], v206 offset:6688
	ds_read_b128 v[112:115], v206 offset:64
	ds_read_b128 v[120:123], v206 offset:6720
	ds_read_b128 v[116:119], v206 offset:96
	ds_read_b128 v[124:127], v206 offset:6752
	s_and_b32 s16, s3, 3
	s_mulk_i32 s16, 0x5800
	v_add3_u32 v207, s16, v171, v0
	v_mfma_f32_32x32x16_bf16 v[32:47], v[152:155], v[214:217], v[32:47]
	v_exp_f32_e32 v64, v64
	v_exp_f32_e32 v65, v65
	v_mfma_f32_32x32x16_bf16 v[16:31], v[188:191], v[214:217], v[16:31]
	v_exp_f32_e32 v80, v80
	v_exp_f32_e32 v81, v81
	v_pk_add_f32 v[204:205], v[64:65], 0 op_sel_hi:[1,0]
	v_mfma_f32_32x32x16_bf16 v[32:47], v[156:159], v[218:221], v[32:47]
	v_exp_f32_e32 v66, v66
	v_exp_f32_e32 v67, v67
	v_pk_add_f32 v[204:205], v[80:81], v[204:205]
	v_mfma_f32_32x32x16_bf16 v[16:31], v[192:195], v[218:221], v[16:31]
	v_exp_f32_e32 v82, v82
	v_exp_f32_e32 v83, v83
	v_pk_add_f32 v[204:205], v[66:67], v[204:205]
	v_mfma_f32_32x32x16_bf16 v[32:47], v[160:163], v[222:225], v[32:47]
	v_exp_f32_e32 v68, v68
	v_exp_f32_e32 v69, v69
	v_pk_add_f32 v[204:205], v[82:83], v[204:205]
	v_mfma_f32_32x32x16_bf16 v[16:31], v[196:199], v[222:225], v[16:31]
	v_exp_f32_e32 v84, v84
	v_exp_f32_e32 v85, v85
	v_pk_add_f32 v[204:205], v[68:69], v[204:205]
	v_mfma_f32_32x32x16_bf16 v[32:47], v[164:167], v[226:229], v[32:47]
	v_exp_f32_e32 v70, v70
	v_exp_f32_e32 v71, v71
	v_pk_add_f32 v[204:205], v[84:85], v[204:205]
	v_mfma_f32_32x32x16_bf16 v[16:31], v[200:203], v[226:229], v[16:31]
	v_exp_f32_e32 v86, v86
	v_exp_f32_e32 v87, v87
	v_pk_add_f32 v[204:205], v[70:71], v[204:205]
	ds_read_b128 v[152:155], v207 offset:13312
	ds_read_b128 v[156:159], v207 offset:13344
	ds_read_b128 v[160:163], v207 offset:13376
	ds_read_b128 v[164:167], v207 offset:13408
	s_waitcnt lgkmcnt(8)
	v_mfma_f32_32x32x16_bf16 v[214:229], v[96:99], v[2:5], v[48:63]
	v_exp_f32_e32 v72, v72
	v_exp_f32_e32 v73, v73
	v_pk_add_f32 v[204:205], v[86:87], v[204:205]
	v_mfma_f32_32x32x16_bf16 v[230:245], v[104:107], v[2:5], v[48:63]
	v_exp_f32_e32 v88, v88
	v_exp_f32_e32 v89, v89
	v_pk_add_f32 v[204:205], v[72:73], v[204:205]
	v_mfma_f32_32x32x16_bf16 v[214:229], v[100:103], v[6:9], v[214:229]
	v_exp_f32_e32 v74, v74
	v_exp_f32_e32 v75, v75
	v_pk_add_f32 v[204:205], v[88:89], v[204:205]
	v_mfma_f32_32x32x16_bf16 v[230:245], v[108:111], v[6:9], v[230:245]
	v_exp_f32_e32 v90, v90
	v_exp_f32_e32 v91, v91
	v_pk_add_f32 v[204:205], v[74:75], v[204:205]
	ds_read_b128 v[96:99], v206 offset:128
	ds_read_b128 v[104:107], v206 offset:6784
	ds_read_b128 v[100:103], v206 offset:160
	ds_read_b128 v[108:111], v206 offset:6816
	s_waitcnt lgkmcnt(8)
	v_mfma_f32_32x32x16_bf16 v[214:229], v[112:115], v[10:13], v[214:229]
	v_exp_f32_e32 v76, v76
	v_exp_f32_e32 v77, v77
	v_pk_add_f32 v[204:205], v[90:91], v[204:205]
	v_mfma_f32_32x32x16_bf16 v[230:245], v[120:123], v[10:13], v[230:245]
	v_exp_f32_e32 v92, v92
	v_exp_f32_e32 v93, v93
	v_pk_add_f32 v[204:205], v[76:77], v[204:205]
	v_mfma_f32_32x32x16_bf16 v[214:229], v[116:119], v[128:131], v[214:229]
	v_exp_f32_e32 v78, v78
	v_exp_f32_e32 v79, v79
	v_pk_add_f32 v[204:205], v[92:93], v[204:205]
	v_mfma_f32_32x32x16_bf16 v[230:245], v[124:127], v[128:131], v[230:245]
	v_exp_f32_e32 v94, v94
	v_exp_f32_e32 v95, v95
	v_pk_add_f32 v[204:205], v[78:79], v[204:205]
	ds_read_b128 v[188:191], v207 offset:17920
	ds_read_b128 v[192:195], v207 offset:17952
	ds_read_b128 v[196:199], v207 offset:17984
	ds_read_b128 v[200:203], v207 offset:18016
	s_waitcnt lgkmcnt(4)
	v_mfma_f32_32x32x16_bf16 v[214:229], v[96:99], v[132:135], v[214:229]
	s_nop 0
	v_pk_add_f32 v[204:205], v[94:95], v[204:205]
	v_cvt_pk_bf16_f32 v64, v64, v65
	v_cvt_pk_bf16_f32 v65, v66, v67
	v_cvt_pk_bf16_f32 v66, v68, v69
	v_mfma_f32_32x32x16_bf16 v[230:245], v[104:107], v[132:135], v[230:245]
	v_cvt_pk_bf16_f32 v67, v70, v71
	v_cvt_pk_bf16_f32 v68, v72, v73
	v_cvt_pk_bf16_f32 v69, v74, v75
	v_cvt_pk_bf16_f32 v70, v76, v77
	v_cvt_pk_bf16_f32 v71, v78, v79
	v_mfma_f32_32x32x16_bf16 v[214:229], v[100:103], v[136:139], v[214:229]
	v_cvt_pk_bf16_f32 v72, v80, v81
	v_cvt_pk_bf16_f32 v73, v82, v83
	v_cvt_pk_bf16_f32 v74, v84, v85
	v_cvt_pk_bf16_f32 v75, v86, v87
	v_cvt_pk_bf16_f32 v76, v88, v89
	v_mfma_f32_32x32x16_bf16 v[230:245], v[108:111], v[136:139], v[230:245]
	v_cvt_pk_bf16_f32 v77, v90, v91
	v_cvt_pk_bf16_f32 v78, v92, v93
	v_cvt_pk_bf16_f32 v79, v94, v95
	v_add_f32_e32 v208, v204, v205
	v_add_f32_e32 v175, v175, v208
	s_branch .Lq_tail0
.Lq_gen0:
	s_add_i32 s13, s3, 1
	s_cmp_ge_i32 s13, s20
	s_cbranch_scc1 .Lq_nokr_p0
	s_add_i32 s12, s3, 1
	s_and_b32 s12, s12, 3
	s_mulk_i32 s12, 0x5800
	v_add3_u32 v206, s12, v169, v0
	ds_read_b128 v[96:99], v206
	ds_read_b128 v[104:107], v206 offset:6656
	ds_read_b128 v[100:103], v206 offset:32
	ds_read_b128 v[108:111], v206 offset:6688
	ds_read_b128 v[112:115], v206 offset:64
	ds_read_b128 v[120:123], v206 offset:6720
	ds_read_b128 v[116:119], v206 offset:96
	ds_read_b128 v[124:127], v206 offset:6752
.Lq_nokr_p0:
	s_cmp_eq_u32 s3, 0
	s_cbranch_scc1 .Lq_nopv_p0
	s_cmp_gt_i32 s3, s20
	s_cbranch_scc1 .Lq_nopv_p0
	s_waitcnt lgkmcnt(8)
	v_mfma_f32_32x32x16_bf16 v[32:47], v[152:155], v[214:217], v[32:47]
	v_mfma_f32_32x32x16_bf16 v[16:31], v[188:191], v[214:217], v[16:31]
	v_mfma_f32_32x32x16_bf16 v[32:47], v[156:159], v[218:221], v[32:47]
	v_mfma_f32_32x32x16_bf16 v[16:31], v[192:195], v[218:221], v[16:31]
	v_mfma_f32_32x32x16_bf16 v[32:47], v[160:163], v[222:225], v[32:47]
	v_mfma_f32_32x32x16_bf16 v[16:31], v[196:199], v[222:225], v[16:31]
	v_mfma_f32_32x32x16_bf16 v[32:47], v[164:167], v[226:229], v[32:47]
	v_mfma_f32_32x32x16_bf16 v[16:31], v[200:203], v[226:229], v[16:31]
; template <int DQK, int DV, int FLAGS, int qp, int kp, int vts, int op> ...
;     ...
;             bf16x8 vf[2][4];
; #pragma unroll
;             for (int ks = 0; ks < 4; ++ks) vf[0][ks] = *(const LAS bf16x8*)(vb + ks * 32);
;             __builtin_amdgcn_sched_barrier(0);
;             bool need_mask = false;
;             if (FLAGS & AF_CAUSAL) need_mask = need_mask || (kv0 + 63 > qmin_w);
;             if (FLAGS & AF_WINDOW) need_mask = need_mask || (kv0 < qmax_w - (SWA_W - 1));
;             if (need_mask) {
; #pragma unroll
;                 for (int r = 0; r < 16; ++r) { const int c = 16 * (r >> 3) + (r & 7);
;                     bool m0 = false, m1 = false;
;                     if (FLAGS & AF_CAUSAL) { m0 = m0 || (c > nrel); m1 = m1 || (c + 32 > nrel); }
;                     if (FLAGS & AF_WINDOW) { m0 = m0 || (c <= nrel - SWA_W); m1 = m1 || (c + 32 <= nrel - SWA_W); }
;                     if (m0) p0[r] = -INFINITY; if (m1) p1[r] = -INFINITY; }
;             }
;             float mx = 0.f;
;             if ((FLAGS & AF_ROBUST) || !started || !skipmax) {
;               float a = MX3(p0[0], p0[1], p1[0]), b = MX3(p0[2], p0[3], p1[1]); a = MX3(a, p1[2], p1[3]);
; #pragma unroll
;               for (int r = 4; r < 16; r += 4) { a = MX3(a, p0[r], p0[r + 1]); b = MX3(b, p0[r + 2], p0[r + 3]); a = MX3(a, p1[r], p1[r + 1]); b = MX3(b, p1[r + 2], p1[r + 3]); }
;               mx = __builtin_fmaxf(a, b);
;               if ((FLAGS & AF_ROBUST) || !started) mx = __builtin_fmaxf(mx, shfl_xor_l(mx, 32, lane)); }
;             if (FLAGS & AF_ROBUST) {
;                 if (__any(mx > m + 8.0f)) {
;                     const float mn = fmaxf(m, mx), alpha = __builtin_amdgcn_exp2f(m - mn);
;                     l *= alpha; m = mn;
; #pragma unroll
;                     for (int d = 0; d < NDB; ++d)
; #pragma unroll
;                         for (int r = 0; r < 16; ++r) o[d][r] *= alpha;
;                 }
; #pragma unroll
;                 for (int r = 0; r < 16; ++r) { p0[r] -= m; p1[r] -= m; }
;             } else {
;                 if (!started) {
;                     started = true;
;                     m = mx;
; #pragma unroll
;                     for (int r = 0; r < 16; ++r) { p0[r] -= mx; p1[r] -= mx; }
;                     if (!(FLAGS & AF_ALIBI)) {
; #pragma unroll
;                         for (int r = 0; r < 16; ++r) negm[r] = -m;
.Lq_nopv_p0:
	s_cmp_ge_i32 s3, s20
	s_cbranch_scc1 .Lq_nosm_p0
	s_and_b32 s16, s3, 3
	s_mulk_i32 s16, 0x5800
	v_add3_u32 v207, s16, v171, v0
	ds_read_b128 v[152:155], v207 offset:13312
	ds_read_b128 v[156:159], v207 offset:13344
	ds_read_b128 v[160:163], v207 offset:13376
	ds_read_b128 v[164:167], v207 offset:13408
	ds_read_b128 v[188:191], v207 offset:17920
	ds_read_b128 v[192:195], v207 offset:17952
	ds_read_b128 v[196:199], v207 offset:17984
	ds_read_b128 v[200:203], v207 offset:18016
	s_nop 7
	s_nop 7
	s_add_i32 s12, s3, 1
	s_cmp_lg_u32 s12, s20
	s_cbranch_scc1 .Lq_nomask_p0
	s_lshl_b32 s12, s3, 6
	v_subrev_u32_e32 v208, s12, v173
	v_cmp_gt_i32_e64 s[40:41], 0, v208
	v_cmp_gt_i32_e64 s[42:43], 1, v208
	v_cmp_gt_i32_e64 s[44:45], 2, v208
	v_cmp_gt_i32_e64 s[46:47], 3, v208
	v_cndmask_b32_e64 v64, v64, v182, s[40:41]
	v_cmp_gt_i32_e64 s[40:41], 4, v208
	v_cndmask_b32_e64 v65, v65, v182, s[42:43]
	v_cmp_gt_i32_e64 s[42:43], 5, v208
	v_cndmask_b32_e64 v66, v66, v182, s[44:45]
	v_cmp_gt_i32_e64 s[44:45], 6, v208
	v_cndmask_b32_e64 v67, v67, v182, s[46:47]
	v_cmp_gt_i32_e64 s[46:47], 7, v208
	v_cndmask_b32_e64 v68, v68, v182, s[40:41]
	v_cmp_gt_i32_e64 s[40:41], 16, v208
	v_cndmask_b32_e64 v69, v69, v182, s[42:43]
	v_cmp_gt_i32_e64 s[42:43], 17, v208
	v_cndmask_b32_e64 v70, v70, v182, s[44:45]
	v_cmp_gt_i32_e64 s[44:45], 18, v208
	v_cndmask_b32_e64 v71, v71, v182, s[46:47]
	v_cmp_gt_i32_e64 s[46:47], 19, v208
	v_cndmask_b32_e64 v72, v72, v182, s[40:41]
	v_cmp_gt_i32_e64 s[40:41], 20, v208
	v_cndmask_b32_e64 v73, v73, v182, s[42:43]
	v_cmp_gt_i32_e64 s[42:43], 21, v208
	v_cndmask_b32_e64 v74, v74, v182, s[44:45]
	v_cmp_gt_i32_e64 s[44:45], 22, v208
	v_cndmask_b32_e64 v75, v75, v182, s[46:47]
	v_cmp_gt_i32_e64 s[46:47], 23, v208
	v_cndmask_b32_e64 v76, v76, v182, s[40:41]
	v_cmp_gt_i32_e64 s[40:41], 32, v208
	v_cndmask_b32_e64 v77, v77, v182, s[42:43]
	v_cmp_gt_i32_e64 s[42:43], 33, v208
	v_cndmask_b32_e64 v78, v78, v182, s[44:45]
	v_cmp_gt_i32_e64 s[44:45], 34, v208
	v_cndmask_b32_e64 v79, v79, v182, s[46:47]
	v_cmp_gt_i32_e64 s[46:47], 35, v208
	v_cndmask_b32_e64 v80, v80, v182, s[40:41]
	v_cmp_gt_i32_e64 s[40:41], 36, v208
	v_cndmask_b32_e64 v81, v81, v182, s[42:43]
	v_cmp_gt_i32_e64 s[42:43], 37, v208
	v_cndmask_b32_e64 v82, v82, v182, s[44:45]
	v_cmp_gt_i32_e64 s[44:45], 38, v208
	v_cndmask_b32_e64 v83, v83, v182, s[46:47]
	v_cmp_gt_i32_e64 s[46:47], 39, v208
	v_cndmask_b32_e64 v84, v84, v182, s[40:41]
	v_cmp_gt_i32_e64 s[40:41], 48, v208
	v_cndmask_b32_e64 v85, v85, v182, s[42:43]
	v_cmp_gt_i32_e64 s[42:43], 49, v208
	v_cndmask_b32_e64 v86, v86, v182, s[44:45]
	v_cmp_gt_i32_e64 s[44:45], 50, v208
	v_cndmask_b32_e64 v87, v87, v182, s[46:47]
	v_cmp_gt_i32_e64 s[46:47], 51, v208
	v_cndmask_b32_e64 v88, v88, v182, s[40:41]
	v_cmp_gt_i32_e64 s[40:41], 52, v208
	v_cndmask_b32_e64 v89, v89, v182, s[42:43]
	v_cmp_gt_i32_e64 s[42:43], 53, v208
	v_cndmask_b32_e64 v90, v90, v182, s[44:45]
	v_cmp_gt_i32_e64 s[44:45], 54, v208
	v_cndmask_b32_e64 v91, v91, v182, s[46:47]
	v_cmp_gt_i32_e64 s[46:47], 55, v208
	v_cndmask_b32_e64 v92, v92, v182, s[40:41]
	v_cndmask_b32_e64 v93, v93, v182, s[42:43]
	v_cndmask_b32_e64 v94, v94, v182, s[44:45]
	v_cndmask_b32_e64 v95, v95, v182, s[46:47]
.Lq_nomask_p0:
	s_cmp_lg_u32 s3, 0
	s_cbranch_scc1 .Lq_notfirst_p0
	v_max3_f32 v209, v64, v65, v66
	v_max3_f32 v210, v80, v81, v82
	v_max3_f32 v209, v209, v67, v68
	v_max3_f32 v210, v210, v83, v84
	v_max3_f32 v209, v209, v69, v70
	v_max3_f32 v210, v210, v85, v86
	v_max3_f32 v209, v209, v71, v72
	v_max3_f32 v210, v210, v87, v88
	v_max3_f32 v209, v209, v73, v74
	v_max3_f32 v210, v210, v89, v90
	v_max3_f32 v209, v209, v75, v76
	v_max3_f32 v210, v210, v91, v92
	v_max3_f32 v209, v209, v77, v78
	v_max3_f32 v210, v210, v93, v94
	v_max3_f32 v209, v209, v79, v95
	v_max_f32_e32 v209, v209, v210
	s_nop 1
	ds_bpermute_b32 v210, v15, v209
	s_waitcnt lgkmcnt(0)
	v_max_f32_e32 v183, v209, v210
	v_sub_f32_e32 v64, v64, v183
	v_sub_f32_e32 v80, v80, v183
	v_sub_f32_e32 v65, v65, v183
	v_sub_f32_e32 v81, v81, v183
	v_sub_f32_e32 v66, v66, v183
	v_sub_f32_e32 v82, v82, v183
	v_sub_f32_e32 v67, v67, v183
	v_sub_f32_e32 v83, v83, v183
	v_sub_f32_e32 v68, v68, v183
	v_sub_f32_e32 v84, v84, v183
	v_sub_f32_e32 v69, v69, v183
	v_sub_f32_e32 v85, v85, v183
	v_sub_f32_e32 v70, v70, v183
	v_sub_f32_e32 v86, v86, v183
	v_sub_f32_e32 v71, v71, v183
	v_sub_f32_e32 v87, v87, v183
	v_sub_f32_e32 v72, v72, v183
	v_sub_f32_e32 v88, v88, v183
	v_sub_f32_e32 v73, v73, v183
	v_sub_f32_e32 v89, v89, v183
	v_sub_f32_e32 v74, v74, v183
	v_sub_f32_e32 v90, v90, v183
	v_sub_f32_e32 v75, v75, v183
	v_sub_f32_e32 v91, v91, v183
	v_sub_f32_e32 v76, v76, v183
	v_sub_f32_e32 v92, v92, v183
	v_sub_f32_e32 v77, v77, v183
	v_sub_f32_e32 v93, v93, v183
	v_sub_f32_e32 v78, v78, v183
	v_sub_f32_e32 v94, v94, v183
	v_sub_f32_e32 v79, v79, v183
	v_sub_f32_e32 v95, v95, v183
	v_xor_b32_e32 v48, 0x80000000, v183
	v_mov_b32_e32 v49, v48
	v_mov_b32_e32 v50, v48
	v_mov_b32_e32 v51, v48
	v_mov_b32_e32 v52, v48
	v_mov_b32_e32 v53, v48
	v_mov_b32_e32 v54, v48
	v_mov_b32_e32 v55, v48
	v_mov_b32_e32 v56, v48
	v_mov_b32_e32 v57, v48
	v_mov_b32_e32 v58, v48
	v_mov_b32_e32 v59, v48
	v_mov_b32_e32 v60, v48
	v_mov_b32_e32 v61, v48
	v_mov_b32_e32 v62, v48
	v_mov_b32_e32 v63, v48
; #define LAS __attribute__((address_space(3)))
; template <int DQK, int DV, int FLAGS, int qp, int kp, int vts, int op> ...
;     ...
;             __builtin_amdgcn_sched_barrier(0);
; #pragma unroll
;             for (int c = 0; c < ND0 / 2; ++c) {
;                 if (c + 1 < ND0 / 2) {
; #pragma unroll
;                     for (int i = 0; i < 2; ++i) { kf[(c + 1) & 1][2 * i] = *(const LAS bf16x8*)(kb + (2 * c + 2 + i) * 32); kf[(c + 1) & 1][2 * i + 1] = *(const LAS bf16x8*)(kb + 32 * KROW + (2 * c + 2 + i) * 32); }
;                 }
; #pragma unroll
;                 for (int i = 0; i < 2; ++i) {
;                     p0 = __builtin_amdgcn_mfma_f32_32x32x16_bf16(kf[c & 1][2 * i], qr[2 * c + i], p0, 0, 0, 0);
;                     p1 = __builtin_amdgcn_mfma_f32_32x32x16_bf16(kf[c & 1][2 * i + 1], qr[2 * c + i], p1, 0, 0, 0);
;                 }
;                 __builtin_amdgcn_sched_barrier(0);
;             }
;     ...
;             f32x2 rs2 = {0.f, 0.f};
; #pragma unroll
;             for (int r = 0; r < 16; ++r) { p0[r] = __builtin_amdgcn_exp2f(p0[r]); p1[r] = __builtin_amdgcn_exp2f(p1[r]); }
; #pragma unroll
;             for (int r = 0; r < 16; r += 2) { rs2 += (f32x2){p0[r], p0[r + 1]}; rs2 += (f32x2){p1[r], p1[r + 1]}; }
;             l += rs2.x + rs2.y;
;             bf16x8 pf[4];
;             pf[0] = pack_bf16x8(p0, 0); pf[1] = pack_bf16x8(p0, 8); pf[2] = pack_bf16x8(p1, 0); pf[3] = pack_bf16x8(p1, 8);
;             __builtin_amdgcn_sched_barrier(0);
; #pragma unroll
;             for (int d = 0; d < NDB; ++d) {
;                 if (d + 1 < NDB) {
; #pragma unroll
;                     for (int ks = 0; ks < 4; ++ks) vf[(d + 1) & 1][ks] = *(const LAS bf16x8*)(vb + (d + 1) * 32 * VROW + ks * 32);
;                 }
; #pragma unroll
;                 for (int ks = 0; ks < 4; ++ks) o[d] = __builtin_amdgcn_mfma_f32_32x32x16_bf16(vf[d & 1][ks], pf[ks], o[d], 0, 0, 0);
;                 __builtin_amdgcn_sched_barrier(0);
;             }
;         }
;         if (skip && more) ATT_GLOAD((FLAGS & AF_REV) ? t - 1 : t + 1);
;         if (more) ATT_LSTORE(cur ^ 1);
;         __syncthreads();
.Lq_notfirst_p0:
	v_exp_f32_e32 v64, v64
	v_exp_f32_e32 v65, v65
	v_exp_f32_e32 v80, v80
	v_exp_f32_e32 v81, v81
	v_pk_add_f32 v[204:205], v[64:65], 0 op_sel_hi:[1,0]
	v_exp_f32_e32 v66, v66
	v_exp_f32_e32 v67, v67
	v_pk_add_f32 v[204:205], v[80:81], v[204:205]
	v_exp_f32_e32 v82, v82
	v_exp_f32_e32 v83, v83
	v_pk_add_f32 v[204:205], v[66:67], v[204:205]
	v_exp_f32_e32 v68, v68
	v_exp_f32_e32 v69, v69
	v_pk_add_f32 v[204:205], v[82:83], v[204:205]
	v_exp_f32_e32 v84, v84
	v_exp_f32_e32 v85, v85
	v_pk_add_f32 v[204:205], v[68:69], v[204:205]
	v_exp_f32_e32 v70, v70
	v_exp_f32_e32 v71, v71
	v_pk_add_f32 v[204:205], v[84:85], v[204:205]
	v_exp_f32_e32 v86, v86
	v_exp_f32_e32 v87, v87
	v_pk_add_f32 v[204:205], v[70:71], v[204:205]
	v_exp_f32_e32 v72, v72
	v_exp_f32_e32 v73, v73
	v_pk_add_f32 v[204:205], v[86:87], v[204:205]
	v_exp_f32_e32 v88, v88
	v_exp_f32_e32 v89, v89
	v_pk_add_f32 v[204:205], v[72:73], v[204:205]
	v_exp_f32_e32 v74, v74
	v_exp_f32_e32 v75, v75
	v_pk_add_f32 v[204:205], v[88:89], v[204:205]
	v_exp_f32_e32 v90, v90
	v_exp_f32_e32 v91, v91
	v_pk_add_f32 v[204:205], v[74:75], v[204:205]
	v_exp_f32_e32 v76, v76
	v_exp_f32_e32 v77, v77
	v_pk_add_f32 v[204:205], v[90:91], v[204:205]
	v_exp_f32_e32 v92, v92
	v_exp_f32_e32 v93, v93
	v_pk_add_f32 v[204:205], v[76:77], v[204:205]
	v_exp_f32_e32 v78, v78
	v_exp_f32_e32 v79, v79
	v_pk_add_f32 v[204:205], v[92:93], v[204:205]
	v_exp_f32_e32 v94, v94
	v_exp_f32_e32 v95, v95
	v_pk_add_f32 v[204:205], v[78:79], v[204:205]
	s_nop 0
	v_pk_add_f32 v[204:205], v[94:95], v[204:205]
	v_cvt_pk_bf16_f32 v64, v64, v65
	v_cvt_pk_bf16_f32 v65, v66, v67
	v_cvt_pk_bf16_f32 v66, v68, v69
	v_cvt_pk_bf16_f32 v67, v70, v71
	v_cvt_pk_bf16_f32 v68, v72, v73
	v_cvt_pk_bf16_f32 v69, v74, v75
	v_cvt_pk_bf16_f32 v70, v76, v77
	v_cvt_pk_bf16_f32 v71, v78, v79
	v_cvt_pk_bf16_f32 v72, v80, v81
	v_cvt_pk_bf16_f32 v73, v82, v83
	v_cvt_pk_bf16_f32 v74, v84, v85
	v_cvt_pk_bf16_f32 v75, v86, v87
	v_cvt_pk_bf16_f32 v76, v88, v89
	v_cvt_pk_bf16_f32 v77, v90, v91
	v_cvt_pk_bf16_f32 v78, v92, v93
	v_cvt_pk_bf16_f32 v79, v94, v95
	v_add_f32_e32 v208, v204, v205
	v_add_f32_e32 v175, v175, v208
.Lq_nosm_p0:
	s_cmp_ge_i32 s13, s20
	s_cbranch_scc1 .Lq_noqk_p0
	s_waitcnt lgkmcnt(0)
	v_mfma_f32_32x32x16_bf16 v[214:229], v[96:99], v[2:5], v[48:63]
	v_mfma_f32_32x32x16_bf16 v[230:245], v[104:107], v[2:5], v[48:63]
	v_mfma_f32_32x32x16_bf16 v[214:229], v[100:103], v[6:9], v[214:229]
	v_mfma_f32_32x32x16_bf16 v[230:245], v[108:111], v[6:9], v[230:245]
	v_mfma_f32_32x32x16_bf16 v[214:229], v[112:115], v[10:13], v[214:229]
	v_mfma_f32_32x32x16_bf16 v[230:245], v[120:123], v[10:13], v[230:245]
	v_mfma_f32_32x32x16_bf16 v[214:229], v[116:119], v[128:131], v[214:229]
	v_mfma_f32_32x32x16_bf16 v[230:245], v[124:127], v[128:131], v[230:245]
	ds_read_b128 v[96:99], v206 offset:128
	ds_read_b128 v[104:107], v206 offset:6784
	ds_read_b128 v[100:103], v206 offset:160
	ds_read_b128 v[108:111], v206 offset:6816
	s_waitcnt lgkmcnt(0)
	v_mfma_f32_32x32x16_bf16 v[214:229], v[96:99], v[132:135], v[214:229]
	v_mfma_f32_32x32x16_bf16 v[230:245], v[104:107], v[132:135], v[230:245]
	v_mfma_f32_32x32x16_bf16 v[214:229], v[100:103], v[136:139], v[214:229]
	v_mfma_f32_32x32x16_bf16 v[230:245], v[108:111], v[136:139], v[230:245]
.Lq_noqk_p0:
.Lq_tail0:
	s_add_i32 s12, s3, 2
	s_cmp_ge_i32 s12, s2
	s_cbranch_scc1 .Lq_nols_p0
	s_and_b32 s16, s12, 3
	s_mulk_i32 s16, 0x5800
	s_waitcnt vmcnt(0)
	v_add_u32_e32 v209, s16, v14
	v_add_u32_e32 v210, s16, v174
	v_add_u32_e32 v211, s16, v172
	ds_write_b128 v209, v[140:143]
	ds_write_b128 v210, v[148:151] offset:13312
	s_and_saveexec_b64 s[14:15], s[10:11]
	ds_write_b128 v211, v[144:147]
	s_or_b64 exec, exec, s[14:15]
	s_add_i32 s12, s3, 3
	s_cmp_ge_i32 s12, s2
	s_cbranch_scc1 .Lq_nols_p0
	s_and_saveexec_b64 s[14:15], s[10:11]
	global_load_dwordx4 v[144:147], v[180:181], off
	s_or_b64 exec, exec, s[14:15]
	global_load_dwordx4 v[140:143], v[178:179], off
	global_load_dwordx4 v[148:151], v[176:177], off
	s_mov_b64 s[14:15], 0x80
	v_lshl_add_u64 v[176:177], v[176:177], 0, s[14:15]
	v_lshl_add_u64 v[178:179], v[178:179], 0, s[96:97]
	v_lshl_add_u64 v[180:181], v[180:181], 0, s[96:97]
.Lq_nols_p0:
	s_add_i32 s3, s3, 1
	s_cmp_ge_i32 s3, s2
	s_cbranch_scc1 .Lq_flush1
	s_waitcnt lgkmcnt(0)
	s_barrier
; #define LAS __attribute__((address_space(3)))
; template <int DQK, int DV, int FLAGS, int qp, int kp, int vts, int op> ...
;     ...
;             __builtin_amdgcn_sched_barrier(0);
; #pragma unroll
;             for (int c = 0; c < ND0 / 2; ++c) {
;                 if (c + 1 < ND0 / 2) {
; #pragma unroll
;                     for (int i = 0; i < 2; ++i) { kf[(c + 1) & 1][2 * i] = *(const LAS bf16x8*)(kb + (2 * c + 2 + i) * 32); kf[(c + 1) & 1][2 * i + 1] = *(const LAS bf16x8*)(kb + 32 * KROW + (2 * c + 2 + i) * 32); }
;                 }
; #pragma unroll
;                 for (int i = 0; i < 2; ++i) {
;                     p0 = __builtin_amdgcn_mfma_f32_32x32x16_bf16(kf[c & 1][2 * i], qr[2 * c + i], p0, 0, 0, 0);
;                     p1 = __builtin_amdgcn_mfma_f32_32x32x16_bf16(kf[c & 1][2 * i + 1], qr[2 * c + i], p1, 0, 0, 0);
;                 }
;                 __builtin_amdgcn_sched_barrier(0);
;             }
;             if (more) ATT_GLOAD((FLAGS & AF_REV) ? t - 1 : t + 1);
;     ...
;             f32x2 rs2 = {0.f, 0.f};
; #pragma unroll
;             for (int r = 0; r < 16; ++r) { p0[r] = __builtin_amdgcn_exp2f(p0[r]); p1[r] = __builtin_amdgcn_exp2f(p1[r]); }
; #pragma unroll
;             for (int r = 0; r < 16; r += 2) { rs2 += (f32x2){p0[r], p0[r + 1]}; rs2 += (f32x2){p1[r], p1[r + 1]}; }
;             l += rs2.x + rs2.y;
;             bf16x8 pf[4];
;             pf[0] = pack_bf16x8(p0, 0); pf[1] = pack_bf16x8(p0, 8); pf[2] = pack_bf16x8(p1, 0); pf[3] = pack_bf16x8(p1, 8);
;             __builtin_amdgcn_sched_barrier(0);
; #pragma unroll
;             for (int d = 0; d < NDB; ++d) {
;                 if (d + 1 < NDB) {
; #pragma unroll
;                     for (int ks = 0; ks < 4; ++ks) vf[(d + 1) & 1][ks] = *(const LAS bf16x8*)(vb + (d + 1) * 32 * VROW + ks * 32);
;                 }
; #pragma unroll
;                 for (int ks = 0; ks < 4; ++ks) o[d] = __builtin_amdgcn_mfma_f32_32x32x16_bf16(vf[d & 1][ks], pf[ks], o[d], 0, 0, 0);
;                 __builtin_amdgcn_sched_barrier(0);
;             }
.Lq_top1:
	s_cmp_eq_u32 s3, 0
	s_cbranch_scc1 .Lq_gen1
	s_add_i32 s13, s3, 1
	s_cmp_ge_i32 s13, s20
	s_cbranch_scc1 .Lq_gen1
	s_add_i32 s12, s3, 1
	s_and_b32 s12, s12, 3
	s_mulk_i32 s12, 0x5800
	v_add3_u32 v206, s12, v169, v0
	ds_read_b128 v[96:99], v206
	ds_read_b128 v[104:107], v206 offset:6656
	ds_read_b128 v[100:103], v206 offset:32
	ds_read_b128 v[108:111], v206 offset:6688
	ds_read_b128 v[112:115], v206 offset:64
	ds_read_b128 v[120:123], v206 offset:6720
	ds_read_b128 v[116:119], v206 offset:96
	ds_read_b128 v[124:127], v206 offset:6752
	s_and_b32 s16, s3, 3
	s_mulk_i32 s16, 0x5800
	v_add3_u32 v207, s16, v171, v0
	v_mfma_f32_32x32x16_bf16 v[32:47], v[152:155], v[64:67], v[32:47]
	v_exp_f32_e32 v214, v214
	v_exp_f32_e32 v215, v215
	v_mfma_f32_32x32x16_bf16 v[16:31], v[188:191], v[64:67], v[16:31]
	v_exp_f32_e32 v230, v230
	v_exp_f32_e32 v231, v231
	v_pk_add_f32 v[204:205], v[214:215], 0 op_sel_hi:[1,0]
	v_mfma_f32_32x32x16_bf16 v[32:47], v[156:159], v[68:71], v[32:47]
	v_exp_f32_e32 v216, v216
	v_exp_f32_e32 v217, v217
	v_pk_add_f32 v[204:205], v[230:231], v[204:205]
	v_mfma_f32_32x32x16_bf16 v[16:31], v[192:195], v[68:71], v[16:31]
	v_exp_f32_e32 v232, v232
	v_exp_f32_e32 v233, v233
	v_pk_add_f32 v[204:205], v[216:217], v[204:205]
	v_mfma_f32_32x32x16_bf16 v[32:47], v[160:163], v[72:75], v[32:47]
	v_exp_f32_e32 v218, v218
	v_exp_f32_e32 v219, v219
	v_pk_add_f32 v[204:205], v[232:233], v[204:205]
	v_mfma_f32_32x32x16_bf16 v[16:31], v[196:199], v[72:75], v[16:31]
	v_exp_f32_e32 v234, v234
	v_exp_f32_e32 v235, v235
	v_pk_add_f32 v[204:205], v[218:219], v[204:205]
	v_mfma_f32_32x32x16_bf16 v[32:47], v[164:167], v[76:79], v[32:47]
	v_exp_f32_e32 v220, v220
	v_exp_f32_e32 v221, v221
	v_pk_add_f32 v[204:205], v[234:235], v[204:205]
	v_mfma_f32_32x32x16_bf16 v[16:31], v[200:203], v[76:79], v[16:31]
	v_exp_f32_e32 v236, v236
	v_exp_f32_e32 v237, v237
	v_pk_add_f32 v[204:205], v[220:221], v[204:205]
	ds_read_b128 v[152:155], v207 offset:13312
	ds_read_b128 v[156:159], v207 offset:13344
	ds_read_b128 v[160:163], v207 offset:13376
	ds_read_b128 v[164:167], v207 offset:13408
	s_waitcnt lgkmcnt(8)
	v_mfma_f32_32x32x16_bf16 v[64:79], v[96:99], v[2:5], v[48:63]
	v_exp_f32_e32 v222, v222
	v_exp_f32_e32 v223, v223
	v_pk_add_f32 v[204:205], v[236:237], v[204:205]
	v_mfma_f32_32x32x16_bf16 v[80:95], v[104:107], v[2:5], v[48:63]
	v_exp_f32_e32 v238, v238
	v_exp_f32_e32 v239, v239
	v_pk_add_f32 v[204:205], v[222:223], v[204:205]
	v_mfma_f32_32x32x16_bf16 v[64:79], v[100:103], v[6:9], v[64:79]
	v_exp_f32_e32 v224, v224
	v_exp_f32_e32 v225, v225
	v_pk_add_f32 v[204:205], v[238:239], v[204:205]
	v_mfma_f32_32x32x16_bf16 v[80:95], v[108:111], v[6:9], v[80:95]
	v_exp_f32_e32 v240, v240
	v_exp_f32_e32 v241, v241
	v_pk_add_f32 v[204:205], v[224:225], v[204:205]
	ds_read_b128 v[96:99], v206 offset:128
	ds_read_b128 v[104:107], v206 offset:6784
	ds_read_b128 v[100:103], v206 offset:160
	ds_read_b128 v[108:111], v206 offset:6816
	s_waitcnt lgkmcnt(8)
	v_mfma_f32_32x32x16_bf16 v[64:79], v[112:115], v[10:13], v[64:79]
	v_exp_f32_e32 v226, v226
	v_exp_f32_e32 v227, v227
	v_pk_add_f32 v[204:205], v[240:241], v[204:205]
	v_mfma_f32_32x32x16_bf16 v[80:95], v[120:123], v[10:13], v[80:95]
	v_exp_f32_e32 v242, v242
	v_exp_f32_e32 v243, v243
	v_pk_add_f32 v[204:205], v[226:227], v[204:205]
	v_mfma_f32_32x32x16_bf16 v[64:79], v[116:119], v[128:131], v[64:79]
	v_exp_f32_e32 v228, v228
	v_exp_f32_e32 v229, v229
	v_pk_add_f32 v[204:205], v[242:243], v[204:205]
	v_mfma_f32_32x32x16_bf16 v[80:95], v[124:127], v[128:131], v[80:95]
	v_exp_f32_e32 v244, v244
	v_exp_f32_e32 v245, v245
	v_pk_add_f32 v[204:205], v[228:229], v[204:205]
	ds_read_b128 v[188:191], v207 offset:17920
	ds_read_b128 v[192:195], v207 offset:17952
	ds_read_b128 v[196:199], v207 offset:17984
	ds_read_b128 v[200:203], v207 offset:18016
	s_waitcnt lgkmcnt(4)
	v_mfma_f32_32x32x16_bf16 v[64:79], v[96:99], v[132:135], v[64:79]
	s_nop 0
	v_pk_add_f32 v[204:205], v[244:245], v[204:205]
	v_cvt_pk_bf16_f32 v214, v214, v215
	v_cvt_pk_bf16_f32 v215, v216, v217
	v_cvt_pk_bf16_f32 v216, v218, v219
	v_mfma_f32_32x32x16_bf16 v[80:95], v[104:107], v[132:135], v[80:95]
	v_cvt_pk_bf16_f32 v217, v220, v221
	v_cvt_pk_bf16_f32 v218, v222, v223
	v_cvt_pk_bf16_f32 v219, v224, v225
	v_cvt_pk_bf16_f32 v220, v226, v227
	v_cvt_pk_bf16_f32 v221, v228, v229
	v_mfma_f32_32x32x16_bf16 v[64:79], v[100:103], v[136:139], v[64:79]
	v_cvt_pk_bf16_f32 v222, v230, v231
	v_cvt_pk_bf16_f32 v223, v232, v233
	v_cvt_pk_bf16_f32 v224, v234, v235
	v_cvt_pk_bf16_f32 v225, v236, v237
	v_cvt_pk_bf16_f32 v226, v238, v239
	v_mfma_f32_32x32x16_bf16 v[80:95], v[108:111], v[136:139], v[80:95]
	v_cvt_pk_bf16_f32 v227, v240, v241
	v_cvt_pk_bf16_f32 v228, v242, v243
	v_cvt_pk_bf16_f32 v229, v244, v245
	v_add_f32_e32 v208, v204, v205
	v_add_f32_e32 v175, v175, v208
	s_branch .Lq_tail1

; #define LAS __attribute__((address_space(3)))
; template <int DQK, int DV, int FLAGS, int qp, int kp, int vts, int op> ...
;     ...
;             bf16x8 vf[2][4];
; #pragma unroll
;             for (int ks = 0; ks < 4; ++ks) vf[0][ks] = *(const LAS bf16x8*)(vb + ks * 32);
;             __builtin_amdgcn_sched_barrier(0);
;             bool need_mask = false;
;             if (FLAGS & AF_CAUSAL) need_mask = need_mask || (kv0 + 63 > qmin_w);
;             if (FLAGS & AF_WINDOW) need_mask = need_mask || (kv0 < qmax_w - (SWA_W - 1));
;             if (need_mask) {
; #pragma unroll
;                 for (int r = 0; r < 16; ++r) { const int c = 16 * (r >> 3) + (r & 7);
;                     bool m0 = false, m1 = false;
;                     if (FLAGS & AF_CAUSAL) { m0 = m0 || (c > nrel); m1 = m1 || (c + 32 > nrel); }
;                     if (FLAGS & AF_WINDOW) { m0 = m0 || (c <= nrel - SWA_W); m1 = m1 || (c + 32 <= nrel - SWA_W); }
;                     if (m0) p0[r] = -INFINITY; if (m1) p1[r] = -INFINITY; }
;             }
;     ...
;             __builtin_amdgcn_sched_barrier(0);
; #pragma unroll
;             for (int d = 0; d < NDB; ++d) {
;                 if (d + 1 < NDB) {
; #pragma unroll
;                     for (int ks = 0; ks < 4; ++ks) vf[(d + 1) & 1][ks] = *(const LAS bf16x8*)(vb + (d + 1) * 32 * VROW + ks * 32);
;                 }
; #pragma unroll
;                 for (int ks = 0; ks < 4; ++ks) o[d] = __builtin_amdgcn_mfma_f32_32x32x16_bf16(vf[d & 1][ks], pf[ks], o[d], 0, 0, 0);
;                 __builtin_amdgcn_sched_barrier(0);
;             }
.Lq_nokr_p1:
	s_cmp_eq_u32 s3, 0
	s_cbranch_scc1 .Lq_nopv_p1
	s_cmp_gt_i32 s3, s20
	s_cbranch_scc1 .Lq_nopv_p1
	s_waitcnt lgkmcnt(8)
	v_mfma_f32_32x32x16_bf16 v[32:47], v[152:155], v[64:67], v[32:47]
	v_mfma_f32_32x32x16_bf16 v[16:31], v[188:191], v[64:67], v[16:31]
	v_mfma_f32_32x32x16_bf16 v[32:47], v[156:159], v[68:71], v[32:47]
	v_mfma_f32_32x32x16_bf16 v[16:31], v[192:195], v[68:71], v[16:31]
	v_mfma_f32_32x32x16_bf16 v[32:47], v[160:163], v[72:75], v[32:47]
	v_mfma_f32_32x32x16_bf16 v[16:31], v[196:199], v[72:75], v[16:31]
	v_mfma_f32_32x32x16_bf16 v[32:47], v[164:167], v[76:79], v[32:47]
	v_mfma_f32_32x32x16_bf16 v[16:31], v[200:203], v[76:79], v[16:31]
.Lq_nopv_p1:
	s_cmp_ge_i32 s3, s20
	s_cbranch_scc1 .Lq_nosm_p1
	s_and_b32 s16, s3, 3
	s_mulk_i32 s16, 0x5800
	v_add3_u32 v207, s16, v171, v0
	ds_read_b128 v[152:155], v207 offset:13312
	ds_read_b128 v[156:159], v207 offset:13344
	ds_read_b128 v[160:163], v207 offset:13376
	ds_read_b128 v[164:167], v207 offset:13408
	ds_read_b128 v[188:191], v207 offset:17920
	ds_read_b128 v[192:195], v207 offset:17952
	ds_read_b128 v[196:199], v207 offset:17984
	ds_read_b128 v[200:203], v207 offset:18016
	s_nop 7
	s_nop 7
	s_add_i32 s12, s3, 1
	s_cmp_lg_u32 s12, s20
	s_cbranch_scc1 .Lq_nomask_p1
	s_lshl_b32 s12, s3, 6
	v_subrev_u32_e32 v208, s12, v173
	v_cmp_gt_i32_e64 s[40:41], 0, v208
	v_cmp_gt_i32_e64 s[42:43], 1, v208
	v_cmp_gt_i32_e64 s[44:45], 2, v208
	v_cmp_gt_i32_e64 s[46:47], 3, v208
	v_cndmask_b32_e64 v214, v214, v182, s[40:41]
	v_cmp_gt_i32_e64 s[40:41], 4, v208
	v_cndmask_b32_e64 v215, v215, v182, s[42:43]
	v_cmp_gt_i32_e64 s[42:43], 5, v208
	v_cndmask_b32_e64 v216, v216, v182, s[44:45]
	v_cmp_gt_i32_e64 s[44:45], 6, v208
	v_cndmask_b32_e64 v217, v217, v182, s[46:47]
	v_cmp_gt_i32_e64 s[46:47], 7, v208
	v_cndmask_b32_e64 v218, v218, v182, s[40:41]
	v_cmp_gt_i32_e64 s[40:41], 16, v208
	v_cndmask_b32_e64 v219, v219, v182, s[42:43]
	v_cmp_gt_i32_e64 s[42:43], 17, v208
	v_cndmask_b32_e64 v220, v220, v182, s[44:45]
	v_cmp_gt_i32_e64 s[44:45], 18, v208
	v_cndmask_b32_e64 v221, v221, v182, s[46:47]
	v_cmp_gt_i32_e64 s[46:47], 19, v208
	v_cndmask_b32_e64 v222, v222, v182, s[40:41]
	v_cmp_gt_i32_e64 s[40:41], 20, v208
	v_cndmask_b32_e64 v223, v223, v182, s[42:43]
	v_cmp_gt_i32_e64 s[42:43], 21, v208
	v_cndmask_b32_e64 v224, v224, v182, s[44:45]
	v_cmp_gt_i32_e64 s[44:45], 22, v208
	v_cndmask_b32_e64 v225, v225, v182, s[46:47]
	v_cmp_gt_i32_e64 s[46:47], 23, v208
	v_cndmask_b32_e64 v226, v226, v182, s[40:41]
	v_cmp_gt_i32_e64 s[40:41], 32, v208
	v_cndmask_b32_e64 v227, v227, v182, s[42:43]
	v_cmp_gt_i32_e64 s[42:43], 33, v208
	v_cndmask_b32_e64 v228, v228, v182, s[44:45]
	v_cmp_gt_i32_e64 s[44:45], 34, v208
	v_cndmask_b32_e64 v229, v229, v182, s[46:47]
	v_cmp_gt_i32_e64 s[46:47], 35, v208
	v_cndmask_b32_e64 v230, v230, v182, s[40:41]
	v_cmp_gt_i32_e64 s[40:41], 36, v208
	v_cndmask_b32_e64 v231, v231, v182, s[42:43]
	v_cmp_gt_i32_e64 s[42:43], 37, v208
	v_cndmask_b32_e64 v232, v232, v182, s[44:45]
	v_cmp_gt_i32_e64 s[44:45], 38, v208
	v_cndmask_b32_e64 v233, v233, v182, s[46:47]
	v_cmp_gt_i32_e64 s[46:47], 39, v208
	v_cndmask_b32_e64 v234, v234, v182, s[40:41]
	v_cmp_gt_i32_e64 s[40:41], 48, v208
	v_cndmask_b32_e64 v235, v235, v182, s[42:43]
	v_cmp_gt_i32_e64 s[42:43], 49, v208
	v_cndmask_b32_e64 v236, v236, v182, s[44:45]
	v_cmp_gt_i32_e64 s[44:45], 50, v208
	v_cndmask_b32_e64 v237, v237, v182, s[46:47]
	v_cmp_gt_i32_e64 s[46:47], 51, v208
	v_cndmask_b32_e64 v238, v238, v182, s[40:41]
	v_cmp_gt_i32_e64 s[40:41], 52, v208
	v_cndmask_b32_e64 v239, v239, v182, s[42:43]
	v_cmp_gt_i32_e64 s[42:43], 53, v208
	v_cndmask_b32_e64 v240, v240, v182, s[44:45]
	v_cmp_gt_i32_e64 s[44:45], 54, v208
	v_cndmask_b32_e64 v241, v241, v182, s[46:47]
	v_cmp_gt_i32_e64 s[46:47], 55, v208
	v_cndmask_b32_e64 v242, v242, v182, s[40:41]
	v_cndmask_b32_e64 v243, v243, v182, s[42:43]
	v_cndmask_b32_e64 v244, v244, v182, s[44:45]
	v_cndmask_b32_e64 v245, v245, v182, s[46:47]
; #define MX3(a, b, c) __builtin_fmaxf(__builtin_fmaxf((a), (b)), (c))
; template <int DQK, int DV, int FLAGS, int qp, int kp, int vts, int op> ...
;     ...
;             float mx = 0.f;
;             if ((FLAGS & AF_ROBUST) || !started || !skipmax) {
;               float a = MX3(p0[0], p0[1], p1[0]), b = MX3(p0[2], p0[3], p1[1]); a = MX3(a, p1[2], p1[3]);
; #pragma unroll
;               for (int r = 4; r < 16; r += 4) { a = MX3(a, p0[r], p0[r + 1]); b = MX3(b, p0[r + 2], p0[r + 3]); a = MX3(a, p1[r], p1[r + 1]); b = MX3(b, p1[r + 2], p1[r + 3]); }
;               mx = __builtin_fmaxf(a, b);
;               if ((FLAGS & AF_ROBUST) || !started) mx = __builtin_fmaxf(mx, shfl_xor_l(mx, 32, lane)); }
;             if (FLAGS & AF_ROBUST) {
;                 if (__any(mx > m + 8.0f)) {
;                     const float mn = fmaxf(m, mx), alpha = __builtin_amdgcn_exp2f(m - mn);
;                     l *= alpha; m = mn;
; #pragma unroll
;                     for (int d = 0; d < NDB; ++d)
; #pragma unroll
;                         for (int r = 0; r < 16; ++r) o[d][r] *= alpha;
;                 }
; #pragma unroll
;                 for (int r = 0; r < 16; ++r) { p0[r] -= m; p1[r] -= m; }
;             } else {
;                 if (!started) {
;                     started = true;
;                     m = mx;
; #pragma unroll
;                     for (int r = 0; r < 16; ++r) { p0[r] -= mx; p1[r] -= mx; }
;                     if (!(FLAGS & AF_ALIBI)) {
; #pragma unroll
;                         for (int r = 0; r < 16; ++r) negm[r] = -m;
;                     }
;                 } else if (!skipmax && __any(mx > 64.0f)) {
;                     mx = __builtin_fmaxf(mx, shfl_xor_l(mx, 32, lane));
;                     const float dl = __builtin_fmaxf(mx, 0.f), alpha = __builtin_amdgcn_exp2f(-dl);
;                     m += dl; l *= alpha;
; #pragma unroll
;                     for (int r = 0; r < 16; ++r) { p0[r] -= dl; p1[r] -= dl; }
; #pragma unroll
;                     for (int d = 0; d < NDB; ++d)
; #pragma unroll
;                         for (int r = 0; r < 16; ++r) o[d][r] *= alpha;
;                     if (!(FLAGS & AF_ALIBI)) {
; #pragma unroll
;                         for (int r = 0; r < 16; ++r) negm[r] = -m;
;                     }
;                 }
;             }
;             f32x2 rs2 = {0.f, 0.f};
; #pragma unroll
.Lq_nomask_p1:
	s_cmp_lg_u32 s3, 0
	s_cbranch_scc1 .Lq_notfirst_p1
	v_max3_f32 v209, v214, v215, v216
	v_max3_f32 v210, v230, v231, v232
	v_max3_f32 v209, v209, v217, v218
	v_max3_f32 v210, v210, v233, v234
	v_max3_f32 v209, v209, v219, v220
	v_max3_f32 v210, v210, v235, v236
	v_max3_f32 v209, v209, v221, v222
	v_max3_f32 v210, v210, v237, v238
	v_max3_f32 v209, v209, v223, v224
	v_max3_f32 v210, v210, v239, v240
	v_max3_f32 v209, v209, v225, v226
	v_max3_f32 v210, v210, v241, v242
	v_max3_f32 v209, v209, v227, v228
	v_max3_f32 v210, v210, v243, v244
	v_max3_f32 v209, v209, v229, v245
	v_max_f32_e32 v209, v209, v210
	s_nop 1
	ds_bpermute_b32 v210, v15, v209
	s_waitcnt lgkmcnt(0)
	v_max_f32_e32 v183, v209, v210
	v_sub_f32_e32 v214, v214, v183
	v_sub_f32_e32 v230, v230, v183
	v_sub_f32_e32 v215, v215, v183
	v_sub_f32_e32 v231, v231, v183
	v_sub_f32_e32 v216, v216, v183
	v_sub_f32_e32 v232, v232, v183
	v_sub_f32_e32 v217, v217, v183
	v_sub_f32_e32 v233, v233, v183
	v_sub_f32_e32 v218, v218, v183
	v_sub_f32_e32 v234, v234, v183
	v_sub_f32_e32 v219, v219, v183
	v_sub_f32_e32 v235, v235, v183
	v_sub_f32_e32 v220, v220, v183
	v_sub_f32_e32 v236, v236, v183
	v_sub_f32_e32 v221, v221, v183
	v_sub_f32_e32 v237, v237, v183
	v_sub_f32_e32 v222, v222, v183
	v_sub_f32_e32 v238, v238, v183
	v_sub_f32_e32 v223, v223, v183
	v_sub_f32_e32 v239, v239, v183
	v_sub_f32_e32 v224, v224, v183
	v_sub_f32_e32 v240, v240, v183
	v_sub_f32_e32 v225, v225, v183
	v_sub_f32_e32 v241, v241, v183
	v_sub_f32_e32 v226, v226, v183
	v_sub_f32_e32 v242, v242, v183
	v_sub_f32_e32 v227, v227, v183
	v_sub_f32_e32 v243, v243, v183
	v_sub_f32_e32 v228, v228, v183
	v_sub_f32_e32 v244, v244, v183
	v_sub_f32_e32 v229, v229, v183
	v_sub_f32_e32 v245, v245, v183
	v_xor_b32_e32 v48, 0x80000000, v183
	v_mov_b32_e32 v49, v48
	v_mov_b32_e32 v50, v48
	v_mov_b32_e32 v51, v48
	v_mov_b32_e32 v52, v48
	v_mov_b32_e32 v53, v48
	v_mov_b32_e32 v54, v48
	v_mov_b32_e32 v55, v48
	v_mov_b32_e32 v56, v48
	v_mov_b32_e32 v57, v48
	v_mov_b32_e32 v58, v48
	v_mov_b32_e32 v59, v48
	v_mov_b32_e32 v60, v48
	v_mov_b32_e32 v61, v48
	v_mov_b32_e32 v62, v48
	v_mov_b32_e32 v63, v48
.Lq_notfirst_p1:
	v_exp_f32_e32 v214, v214
	v_exp_f32_e32 v215, v215
	v_exp_f32_e32 v230, v230
	v_exp_f32_e32 v231, v231
	v_pk_add_f32 v[204:205], v[214:215], 0 op_sel_hi:[1,0]
	v_exp_f32_e32 v216, v216
	v_exp_f32_e32 v217, v217
	v_pk_add_f32 v[204:205], v[230:231], v[204:205]
	v_exp_f32_e32 v232, v232
	v_exp_f32_e32 v233, v233
	v_pk_add_f32 v[204:205], v[216:217], v[204:205]
	v_exp_f32_e32 v218, v218
	v_exp_f32_e32 v219, v219
	v_pk_add_f32 v[204:205], v[232:233], v[204:205]
	v_exp_f32_e32 v234, v234
	v_exp_f32_e32 v235, v235
	v_pk_add_f32 v[204:205], v[218:219], v[204:205]
	v_exp_f32_e32 v220, v220
	v_exp_f32_e32 v221, v221
	v_pk_add_f32 v[204:205], v[234:235], v[204:205]
	v_exp_f32_e32 v236, v236
	v_exp_f32_e32 v237, v237
	v_pk_add_f32 v[204:205], v[220:221], v[204:205]
	v_exp_f32_e32 v222, v222
	v_exp_f32_e32 v223, v223
	v_pk_add_f32 v[204:205], v[236:237], v[204:205]
	v_exp_f32_e32 v238, v238
	v_exp_f32_e32 v239, v239
	v_pk_add_f32 v[204:205], v[222:223], v[204:205]
	v_exp_f32_e32 v224, v224
	v_exp_f32_e32 v225, v225
	v_pk_add_f32 v[204:205], v[238:239], v[204:205]
	v_exp_f32_e32 v240, v240
	v_exp_f32_e32 v241, v241
	v_pk_add_f32 v[204:205], v[224:225], v[204:205]
	v_exp_f32_e32 v226, v226
	v_exp_f32_e32 v227, v227
	v_pk_add_f32 v[204:205], v[240:241], v[204:205]
	v_exp_f32_e32 v242, v242
	v_exp_f32_e32 v243, v243
	v_pk_add_f32 v[204:205], v[226:227], v[204:205]
	v_exp_f32_e32 v228, v228
	v_exp_f32_e32 v229, v229
	v_pk_add_f32 v[204:205], v[242:243], v[204:205]
	v_exp_f32_e32 v244, v244
	v_exp_f32_e32 v245, v245
	v_pk_add_f32 v[204:205], v[228:229], v[204:205]
	s_nop 0
	v_pk_add_f32 v[204:205], v[244:245], v[204:205]
	v_cvt_pk_bf16_f32 v214, v214, v215
	v_cvt_pk_bf16_f32 v215, v216, v217
	v_cvt_pk_bf16_f32 v216, v218, v219
	v_cvt_pk_bf16_f32 v217, v220, v221
	v_cvt_pk_bf16_f32 v218, v222, v223
	v_cvt_pk_bf16_f32 v219, v224, v225
	v_cvt_pk_bf16_f32 v220, v226, v227
	v_cvt_pk_bf16_f32 v221, v228, v229
	v_cvt_pk_bf16_f32 v222, v230, v231
	v_cvt_pk_bf16_f32 v223, v232, v233
	v_cvt_pk_bf16_f32 v224, v234, v235
	v_cvt_pk_bf16_f32 v225, v236, v237
	v_cvt_pk_bf16_f32 v226, v238, v239
	v_cvt_pk_bf16_f32 v227, v240, v241
	v_cvt_pk_bf16_f32 v228, v242, v243
	v_cvt_pk_bf16_f32 v229, v244, v245
	v_add_f32_e32 v208, v204, v205
	v_add_f32_e32 v175, v175, v208
.Lq_nosm_p1:
	s_cmp_ge_i32 s13, s20
	s_cbranch_scc1 .Lq_noqk_p1
	s_waitcnt lgkmcnt(0)
	v_mfma_f32_32x32x16_bf16 v[64:79], v[96:99], v[2:5], v[48:63]
	v_mfma_f32_32x32x16_bf16 v[80:95], v[104:107], v[2:5], v[48:63]
	v_mfma_f32_32x32x16_bf16 v[64:79], v[100:103], v[6:9], v[64:79]
	v_mfma_f32_32x32x16_bf16 v[80:95], v[108:111], v[6:9], v[80:95]
	v_mfma_f32_32x32x16_bf16 v[64:79], v[112:115], v[10:13], v[64:79]
	v_mfma_f32_32x32x16_bf16 v[80:95], v[120:123], v[10:13], v[80:95]
	v_mfma_f32_32x32x16_bf16 v[64:79], v[116:119], v[128:131], v[64:79]
	v_mfma_f32_32x32x16_bf16 v[80:95], v[124:127], v[128:131], v[80:95]
	ds_read_b128 v[96:99], v206 offset:128
	ds_read_b128 v[104:107], v206 offset:6784
	ds_read_b128 v[100:103], v206 offset:160
	ds_read_b128 v[108:111], v206 offset:6816
	s_waitcnt lgkmcnt(0)
	v_mfma_f32_32x32x16_bf16 v[64:79], v[96:99], v[132:135], v[64:79]
	v_mfma_f32_32x32x16_bf16 v[80:95], v[104:107], v[132:135], v[80:95]
	v_mfma_f32_32x32x16_bf16 v[64:79], v[100:103], v[136:139], v[64:79]
	v_mfma_f32_32x32x16_bf16 v[80:95], v[108:111], v[136:139], v[80:95]

; #define LAS __attribute__((address_space(3)))
; #define ATT_LSTORE(buf) do { LAS unsigned char* b_ = lds + (buf) * BUF; \
;         _Pragma("unroll") for (int i = 0; i < KPT; ++i) { if (KCH % NTHREADS == 0 || tid + i * NTHREADS < KCH) *(LAS u32x4*)(b_ + klo[i]) = kreg[i]; } \
;         _Pragma("unroll") for (int i = 0; i < VPT; ++i) *(LAS u32x4*)(b_ + vlo[i]) = vreg[i]; } while (0)
; template <int DQK, int DV, int FLAGS, int qp, int kp, int vts, int op> ...
;     ...
;             __builtin_amdgcn_sched_barrier(0);
; #pragma unroll
;             for (int d = 0; d < NDB; ++d) {
;                 if (d + 1 < NDB) {
; #pragma unroll
;                     for (int ks = 0; ks < 4; ++ks) vf[(d + 1) & 1][ks] = *(const LAS bf16x8*)(vb + (d + 1) * 32 * VROW + ks * 32);
;                 }
; #pragma unroll
;                 for (int ks = 0; ks < 4; ++ks) o[d] = __builtin_amdgcn_mfma_f32_32x32x16_bf16(vf[d & 1][ks], pf[ks], o[d], 0, 0, 0);
;                 __builtin_amdgcn_sched_barrier(0);
;             }
;         }
;         if (skip && more) ATT_GLOAD((FLAGS & AF_REV) ? t - 1 : t + 1);
;         if (more) ATT_LSTORE(cur ^ 1);
;         __syncthreads();
;     }
.Lq_nols_p1:
	s_add_i32 s3, s3, 1
	s_cmp_ge_i32 s3, s2
	s_cbranch_scc1 .Lq_flush0
	s_waitcnt lgkmcnt(0)
	s_barrier
	s_branch .Lq_top0
.Lq_flush0:
	s_cmp_lt_i32 s20, s2
	s_cbranch_scc1 .LBB0_572
	s_waitcnt lgkmcnt(0)
	v_mfma_f32_32x32x16_bf16 v[32:47], v[152:155], v[214:217], v[32:47]
	v_mfma_f32_32x32x16_bf16 v[16:31], v[188:191], v[214:217], v[16:31]
	v_mfma_f32_32x32x16_bf16 v[32:47], v[156:159], v[218:221], v[32:47]
	v_mfma_f32_32x32x16_bf16 v[16:31], v[192:195], v[218:221], v[16:31]
	v_mfma_f32_32x32x16_bf16 v[32:47], v[160:163], v[222:225], v[32:47]
	v_mfma_f32_32x32x16_bf16 v[16:31], v[196:199], v[222:225], v[16:31]
	v_mfma_f32_32x32x16_bf16 v[32:47], v[164:167], v[226:229], v[32:47]
	v_mfma_f32_32x32x16_bf16 v[16:31], v[200:203], v[226:229], v[16:31]
	s_branch .LBB0_572
.Lq_flush1:
	s_cmp_lt_i32 s20, s2
	s_cbranch_scc1 .LBB0_572
	s_waitcnt lgkmcnt(0)
	v_mfma_f32_32x32x16_bf16 v[32:47], v[152:155], v[64:67], v[32:47]
	v_mfma_f32_32x32x16_bf16 v[16:31], v[188:191], v[64:67], v[16:31]
	v_mfma_f32_32x32x16_bf16 v[32:47], v[156:159], v[68:71], v[32:47]
	v_mfma_f32_32x32x16_bf16 v[16:31], v[192:195], v[68:71], v[16:31]
	v_mfma_f32_32x32x16_bf16 v[32:47], v[160:163], v[72:75], v[32:47]
	v_mfma_f32_32x32x16_bf16 v[16:31], v[196:199], v[72:75], v[16:31]
	v_mfma_f32_32x32x16_bf16 v[32:47], v[164:167], v[76:79], v[32:47]
	v_mfma_f32_32x32x16_bf16 v[16:31], v[200:203], v[76:79], v[16:31]
	s_branch .LBB0_572
.Lq_fallback:
	s_branch .LBB0_540
